# v109 + P2 l2norm 1/sqrt via v_rsq_f32 instead of the IEEE sqrt+div expansion (2 per thread and chunk)
# baseline (speedup 1.0000x reference)
; __device__ __forceinline__ void gdn_prep_wg(const bf16* P, const float* SMALL, const float* conv_w, const float* a_log, const float* dt_bias,
;                                             unsigned char* REC, bf16* UF, float* EG, LAS unsigned char* lds, int bh, int n0, int nch) {
;     ...
;                     if (t - 3 + i >= 0) { const LAS unsigned char* src = raw + (row + i) * RAWP + ten * 256 + c0 * 2; const v4u x0 = *(const LAS v4u*)src, x1 = *(const LAS v4u*)(src + 16);
;                         const float* w = conv_w + (size_t)i * CONVW + pcol;
;                         const f32x4 w0 = *(const f32x4*)w, w1 = *(const f32x4*)(w + 4), w2 = *(const f32x4*)(w + 8), w3 = *(const f32x4*)(w + 12);
;                         acc[0] += w0.x * bflo(x0.x); acc[1] += w0.y * bfhi(x0.x); acc[2] += w0.z * bflo(x0.y); acc[3] += w0.w * bfhi(x0.y);
;                         acc[4] += w1.x * bflo(x0.z); acc[5] += w1.y * bfhi(x0.z); acc[6] += w1.z * bflo(x0.w); acc[7] += w1.w * bfhi(x0.w);
;                         acc[8] += w2.x * bflo(x1.x); acc[9] += w2.y * bfhi(x1.x); acc[10] += w2.z * bflo(x1.y); acc[11] += w2.w * bfhi(x1.y);
;                         acc[12] += w3.x * bflo(x1.z); acc[13] += w3.y * bfhi(x1.z); acc[14] += w3.z * bflo(x1.w); acc[15] += w3.w * bfhi(x1.w); } }
;                 float ss = 0.f;
; #pragma unroll
;                 for (int j = 0; j < 16; ++j) { acc[j] = silu_fast(acc[j]); ss += acc[j] * acc[j]; }
;                 if (ten < 2) { ss = sum8(ss); const float s_ = (1.0f / sqrtf(ss + EPS)) * (ten == 0 ? 0.08838834764831845f : 1.0f);
; #pragma unroll
;                     for (int j = 0; j < 16; ++j) acc[j] *= s_; }
;                 if (ten == 0) {
;                     v4u o0, o1; o0.x = pk2(acc[0], acc[1]); o0.y = pk2(acc[2], acc[3]); o0.z = pk2(acc[4], acc[5]); o0.w = pk2(acc[6], acc[7]);
;                     o1.x = pk2(acc[8], acc[9]); o1.y = pk2(acc[10], acc[11]); o1.z = pk2(acc[12], acc[13]); o1.w = pk2(acc[14], acc[15]);
;                     *(LAS v4u*)(qb + row * 272 + c0 * 2) = o0; *(LAS v4u*)(qb + row * 272 + c0 * 2 + 16) = o1;
;                     unsigned char* dst = rec + GR_Q + ((row >> 4) * 4 + (c0 >> 5)) * 1024 + ((c0 >> 4) & 1) * 8;
; #pragma unroll
;                     for (int i = 0; i < 4; ++i) { v2u w; w.x = pk2(acc[4 * i] * egc, acc[4 * i + 1] * egc); w.y = pk2(acc[4 * i + 2] * egc, acc[4 * i + 3] * egc);
.LBB0_332:
	s_or_b64 exec, exec, s[90:91]
	ds_read_b128 v[2:5], v230 offset:1536
	ds_read_b128 v[10:13], v230 offset:1552
	ds_read_b128 v[38:41], v230 offset:1568
	ds_read_b128 v[34:37], v230 offset:1584
	ds_read_b128 v[6:9], v201 offset:2352
	ds_read_b128 v[44:47], v201 offset:2368
	v_add_u32_e32 v43, v155, v154
	s_waitcnt lgkmcnt(0)
	v_lshlrev_b32_e32 v28, 16, v47
	v_and_b32_e32 v29, 0xffff0000, v47
	s_waitcnt vmcnt(0) lgkmcnt(0)
	v_pk_fma_f32 v[24:25], v[36:37], v[28:29], v[24:25]
	v_lshlrev_b32_e32 v36, 16, v46
	v_and_b32_e32 v37, 0xffff0000, v46
	v_pk_fma_f32 v[30:31], v[34:35], v[36:37], v[30:31]
	v_lshlrev_b32_e32 v36, 16, v45
	v_and_b32_e32 v37, 0xffff0000, v45
	v_pk_fma_f32 v[32:33], v[40:41], v[36:37], v[32:33]
	v_lshlrev_b32_e32 v40, 16, v44
	v_and_b32_e32 v41, 0xffff0000, v44
	v_pk_fma_f32 v[26:27], v[38:39], v[40:41], v[26:27]
	v_lshlrev_b32_e32 v40, 16, v9
	v_and_b32_e32 v41, 0xffff0000, v9
	v_pk_fma_f32 v[12:13], v[12:13], v[40:41], v[22:23]
	v_lshlrev_b32_e32 v40, 16, v8
	v_mul_f32_e32 v9, 0xbfb8aa3b, v12
	v_exp_f32_e32 v9, v9
	v_and_b32_e32 v41, 0xffff0000, v8
	v_mul_f32_e32 v38, 0xbfb8aa3b, v26
	v_mul_f32_e32 v39, 0xbfb8aa3b, v27
	v_add_f32_e32 v9, 1.0, v9
	v_rcp_f32_e32 v22, v9
	v_mul_f32_e32 v9, 0xbfb8aa3b, v13
	v_exp_f32_e32 v9, v9
	v_exp_f32_e32 v38, v38
	v_exp_f32_e32 v39, v39
	v_mul_f32_e32 v36, 0xbfb8aa3b, v32
	v_add_f32_e32 v9, 1.0, v9
	v_rcp_f32_e32 v23, v9
	v_pk_fma_f32 v[8:9], v[10:11], v[40:41], v[20:21]
	v_lshlrev_b32_e32 v20, 16, v7
	v_and_b32_e32 v21, 0xffff0000, v7
	v_pk_fma_f32 v[4:5], v[4:5], v[20:21], v[16:17]
	v_lshlrev_b32_e32 v20, 16, v6
	v_mul_f32_e32 v7, 0xbfb8aa3b, v4
	v_exp_f32_e32 v7, v7
	v_and_b32_e32 v21, 0xffff0000, v6
	v_pk_fma_f32 v[2:3], v[2:3], v[20:21], v[14:15]
	v_mul_f32_e32 v10, 0xbfb8aa3b, v8
	v_add_f32_e32 v7, 1.0, v7
	v_rcp_f32_e32 v16, v7
	v_mul_f32_e32 v7, 0xbfb8aa3b, v5
	v_exp_f32_e32 v7, v7
	v_mul_f32_e32 v6, 0xbfb8aa3b, v2
	v_exp_f32_e32 v6, v6
	v_mul_f32_e32 v11, 0xbfb8aa3b, v9
	v_add_f32_e32 v7, 1.0, v7
	v_rcp_f32_e32 v17, v7
	v_mul_f32_e32 v7, 0xbfb8aa3b, v3
	v_exp_f32_e32 v7, v7
	v_exp_f32_e32 v10, v10
	v_exp_f32_e32 v11, v11
	v_add_f32_e32 v6, 1.0, v6
	v_add_f32_e32 v7, 1.0, v7
	v_rcp_f32_e32 v6, v6
	v_rcp_f32_e32 v7, v7
	v_add_f32_e32 v10, 1.0, v10
	v_add_f32_e32 v11, 1.0, v11
	v_mul_f32_e32 v37, 0xbfb8aa3b, v33
	v_rcp_f32_e32 v10, v10
	v_rcp_f32_e32 v11, v11
	v_exp_f32_e32 v36, v36
	v_exp_f32_e32 v37, v37
	v_pk_mul_f32 v[6:7], v[2:3], v[6:7]
	v_mul_f32_e32 v34, 0xbfb8aa3b, v30
	v_mul_f32_e32 v35, 0xbfb8aa3b, v31
	v_pk_mul_f32 v[4:5], v[4:5], v[16:17]
	v_pk_mul_f32 v[2:3], v[6:7], v[6:7]
	v_exp_f32_e32 v34, v34
	v_exp_f32_e32 v35, v35
	v_add_f32_e32 v38, 1.0, v38
	v_add_f32_e32 v39, 1.0, v39
	v_pk_mul_f32 v[16:17], v[4:5], v[4:5]
	v_add_f32_e32 v2, v2, v3
	v_mul_f32_e32 v28, 0xbfb8aa3b, v24
	v_mul_f32_e32 v29, 0xbfb8aa3b, v25
	v_rcp_f32_e32 v38, v38
	v_rcp_f32_e32 v39, v39
	v_pk_mul_f32 v[8:9], v[8:9], v[10:11]
	v_add_f32_e32 v2, v16, v2
	v_exp_f32_e32 v28, v28
	v_exp_f32_e32 v29, v29
	v_add_f32_e32 v36, 1.0, v36
	v_add_f32_e32 v37, 1.0, v37
	v_pk_mul_f32 v[10:11], v[8:9], v[8:9]
	v_add_f32_e32 v2, v17, v2
	v_rcp_f32_e32 v36, v36
	v_rcp_f32_e32 v37, v37
	v_pk_mul_f32 v[12:13], v[12:13], v[22:23]
	v_add_f32_e32 v2, v10, v2
	v_add_f32_e32 v34, 1.0, v34
	v_add_f32_e32 v35, 1.0, v35
	v_pk_mul_f32 v[22:23], v[12:13], v[12:13]
	v_add_f32_e32 v2, v11, v2
	v_rcp_f32_e32 v34, v34
	v_rcp_f32_e32 v35, v35
	v_pk_mul_f32 v[26:27], v[26:27], v[38:39]
	v_add_f32_e32 v2, v22, v2
	v_add_f32_e32 v28, 1.0, v28
	v_add_f32_e32 v29, 1.0, v29
	v_pk_mul_f32 v[38:39], v[26:27], v[26:27]
	v_add_f32_e32 v2, v23, v2
	v_rcp_f32_e32 v28, v28
	v_rcp_f32_e32 v29, v29
	v_pk_mul_f32 v[32:33], v[32:33], v[36:37]
	v_add_f32_e32 v2, v38, v2
	v_pk_mul_f32 v[36:37], v[32:33], v[32:33]
	v_add_f32_e32 v2, v39, v2
	v_pk_mul_f32 v[30:31], v[30:31], v[34:35]
	v_add_f32_e32 v2, v36, v2
	v_pk_mul_f32 v[34:35], v[30:31], v[30:31]
	v_add_f32_e32 v2, v37, v2
	v_pk_mul_f32 v[24:25], v[24:25], v[28:29]
	v_add_f32_e32 v2, v34, v2
	v_pk_mul_f32 v[28:29], v[24:25], v[24:25]
	v_add_f32_e32 v2, v35, v2
	v_add_f32_e32 v2, v28, v2
	v_add_f32_e32 v2, v29, v2
	s_nop 1
	v_add_f32_dpp v2, v2, v2 quad_perm:[1,0,3,2] row_mask:0xf bank_mask:0xf bound_ctrl:1
	s_nop 1
	v_add_f32_dpp v2, v2, v2 quad_perm:[2,3,0,1] row_mask:0xf bank_mask:0xf bound_ctrl:1
	s_nop 1
	v_add_f32_dpp v2, v2, v2 row_half_mirror row_mask:0xf bank_mask:0xf bound_ctrl:1
	v_add_f32_e32 v2, 0x358637bd, v2
	v_rsq_f32_e32 v3, v2
	v_mov_b32_e32 v2, 0
	v_mov_b32_e32 v34, v2
	v_mov_b32_e32 v35, v2
	v_mul_f32_e32 v10, 0x3db504f3, v3
	v_pk_mul_f32 v[14:15], v[6:7], v[10:11] op_sel_hi:[1,0]
	v_pk_mul_f32 v[16:17], v[4:5], v[10:11] op_sel_hi:[1,0]
	v_pk_mul_f32 v[20:21], v[8:9], v[10:11] op_sel_hi:[1,0]
	v_pk_mul_f32 v[12:13], v[12:13], v[10:11] op_sel_hi:[1,0]
	v_pk_mul_f32 v[22:23], v[26:27], v[10:11] op_sel_hi:[1,0]
	v_pk_mul_f32 v[26:27], v[32:33], v[10:11] op_sel_hi:[1,0]
	v_pk_mul_f32 v[28:29], v[30:31], v[10:11] op_sel_hi:[1,0]
	v_pk_mul_f32 v[24:25], v[24:25], v[10:11] op_sel_hi:[1,0]
	v_cvt_pk_bf16_f32 v4, v14, v15
	v_cvt_pk_bf16_f32 v5, v16, v17
	v_cvt_pk_bf16_f32 v6, v20, v21
	v_cvt_pk_bf16_f32 v7, v12, v13
	v_cvt_pk_bf16_f32 v8, v22, v23
	v_cvt_pk_bf16_f32 v9, v26, v27
	v_cvt_pk_bf16_f32 v10, v28, v29
	v_cvt_pk_bf16_f32 v11, v24, v25
	ds_write_b128 v43, v[4:7] offset:17408
	ds_write_b128 v43, v[8:11] offset:17424
	v_mov_b32_e32 v4, v19
	v_pk_mul_f32 v[6:7], v[4:5], v[14:15] op_sel_hi:[0,1]
	v_pk_mul_f32 v[8:9], v[4:5], v[16:17] op_sel_hi:[0,1]
	v_cvt_pk_bf16_f32 v6, v6, v7
	v_cvt_pk_bf16_f32 v7, v8, v9
	v_lshl_add_u64 v[8:9], v[100:101], 0, s[96:97]
	global_store_dwordx2 v[8:9], v[6:7], off offset:-512
	v_pk_mul_f32 v[6:7], v[4:5], v[20:21] op_sel_hi:[0,1]
	v_pk_mul_f32 v[10:11], v[4:5], v[12:13] op_sel_hi:[0,1]
	v_cvt_pk_bf16_f32 v6, v6, v7
	v_cvt_pk_bf16_f32 v7, v10, v11
	global_store_dwordx2 v[8:9], v[6:7], off offset:-256
	v_pk_mul_f32 v[6:7], v[4:5], v[22:23] op_sel_hi:[0,1]
	v_pk_mul_f32 v[10:11], v[4:5], v[26:27] op_sel_hi:[0,1]
	v_cvt_pk_bf16_f32 v6, v6, v7
	v_cvt_pk_bf16_f32 v7, v10, v11
	global_store_dwordx2 v[8:9], v[6:7], off
	v_pk_mul_f32 v[6:7], v[4:5], v[28:29] op_sel_hi:[0,1]
	v_pk_mul_f32 v[4:5], v[4:5], v[24:25] op_sel_hi:[0,1]
	v_cvt_pk_bf16_f32 v6, v6, v7
	v_cvt_pk_bf16_f32 v7, v4, v5
	v_mov_b32_e32 v3, 0
	v_mov_b32_e32 v14, 0
	v_mov_b32_e32 v15, 0
	v_mov_b32_e32 v16, 0
	v_mov_b32_e32 v17, v2
	v_mov_b32_e32 v22, v2
	v_mov_b32_e32 v23, v2
	v_mov_b32_e32 v24, v2
	v_mov_b32_e32 v25, v2
	v_mov_b32_e32 v28, v2
	v_mov_b32_e32 v29, v2
	v_mov_b32_e32 v30, v2
	v_mov_b32_e32 v31, v2
	v_mov_b32_e32 v26, 0
	v_mov_b32_e32 v27, 0
	global_store_dwordx2 v[8:9], v[6:7], off offset:256
	s_and_saveexec_b64 s[90:91], s[86:87]
	s_cbranch_execnz .LBB0_379
	s_or_b64 exec, exec, s[90:91]
	s_and_saveexec_b64 s[90:91], s[88:89]
	s_cbranch_execnz .LBB0_380

; #define LAS __attribute__((address_space(3)))
; __device__ __forceinline__ float bflo(unsigned w) { return __uint_as_float(w << 16); }
; __device__ __forceinline__ float bfhi(unsigned w) { return __uint_as_float(w & 0xffff0000u); }
; __device__ __forceinline__ float sum8(float v) { v += dppmov<0xB1>(v); v += dppmov<0x4E>(v); v += dppmov<0x141>(v); return v; }
; __device__ __forceinline__ float silu_fast(float x) { return x * __builtin_amdgcn_rcpf(1.0f + __builtin_amdgcn_exp2f(-1.4426950408889634f * x)); }
; __device__ __forceinline__ void gdn_prep_wg(const bf16* P, const float* SMALL, const float* conv_w, const float* a_log, const float* dt_bias,
;                                             unsigned char* REC, bf16* UF, float* EG, LAS unsigned char* lds, int bh, int n0, int nch) {
;     ...
;                     if (t - 3 + i >= 0) { const LAS unsigned char* src = raw + (row + i) * RAWP + ten * 256 + c0 * 2; const v4u x0 = *(const LAS v4u*)src, x1 = *(const LAS v4u*)(src + 16);
;                         const float* w = conv_w + (size_t)i * CONVW + pcol;
;                         const f32x4 w0 = *(const f32x4*)w, w1 = *(const f32x4*)(w + 4), w2 = *(const f32x4*)(w + 8), w3 = *(const f32x4*)(w + 12);
;                         acc[0] += w0.x * bflo(x0.x); acc[1] += w0.y * bfhi(x0.x); acc[2] += w0.z * bflo(x0.y); acc[3] += w0.w * bfhi(x0.y);
;                         acc[4] += w1.x * bflo(x0.z); acc[5] += w1.y * bfhi(x0.z); acc[6] += w1.z * bflo(x0.w); acc[7] += w1.w * bfhi(x0.w);
;                         acc[8] += w2.x * bflo(x1.x); acc[9] += w2.y * bfhi(x1.x); acc[10] += w2.z * bflo(x1.y); acc[11] += w2.w * bfhi(x1.y);
;                         acc[12] += w3.x * bflo(x1.z); acc[13] += w3.y * bfhi(x1.z); acc[14] += w3.z * bflo(x1.w); acc[15] += w3.w * bfhi(x1.w); } }
;                 float ss = 0.f;
; #pragma unroll
;                 for (int j = 0; j < 16; ++j) { acc[j] = silu_fast(acc[j]); ss += acc[j] * acc[j]; }
;                 if (ten < 2) { ss = sum8(ss); const float s_ = (1.0f / sqrtf(ss + EPS)) * (ten == 0 ? 0.08838834764831845f : 1.0f);
; #pragma unroll
;                     for (int j = 0; j < 16; ++j) acc[j] *= s_; }
.LBB0_336:
	s_or_b64 exec, exec, s[90:91]
	ds_read_b128 v[2:5], v230 offset:3584
	ds_read_b128 v[10:13], v230 offset:3600
	ds_read_b128 v[44:47], v230 offset:3616
	ds_read_b128 v[36:39], v230 offset:3632
	ds_read_b128 v[6:9], v201 offset:2608
	ds_read_b128 v[48:51], v201 offset:2624
	v_mul_f32_e32 v19, v18, v19
	v_lshl_add_u64 v[20:21], v[102:103], 0, s[96:97]
	s_waitcnt lgkmcnt(0)
	v_lshlrev_b32_e32 v40, 16, v48
	v_and_b32_e32 v41, 0xffff0000, v48
	v_lshlrev_b32_e32 v32, 16, v51
	v_and_b32_e32 v33, 0xffff0000, v51
	s_waitcnt vmcnt(1) lgkmcnt(0)
	v_pk_fma_f32 v[28:29], v[44:45], v[40:41], v[28:29]
	v_lshlrev_b32_e32 v44, 16, v9
	v_and_b32_e32 v45, 0xffff0000, v9
	v_pk_fma_f32 v[12:13], v[12:13], v[44:45], v[24:25]
	v_lshlrev_b32_e32 v44, 16, v8
	v_mul_f32_e32 v9, 0xbfb8aa3b, v12
	v_exp_f32_e32 v9, v9
	v_and_b32_e32 v45, 0xffff0000, v8
	s_waitcnt vmcnt(0) lgkmcnt(0)
	v_pk_fma_f32 v[26:27], v[38:39], v[32:33], v[26:27]
	v_lshlrev_b32_e32 v38, 16, v50
	v_add_f32_e32 v9, 1.0, v9
	v_rcp_f32_e32 v24, v9
	v_mul_f32_e32 v9, 0xbfb8aa3b, v13
	v_exp_f32_e32 v9, v9
	v_and_b32_e32 v39, 0xffff0000, v50
	v_pk_fma_f32 v[30:31], v[36:37], v[38:39], v[30:31]
	v_lshlrev_b32_e32 v38, 16, v49
	v_add_f32_e32 v9, 1.0, v9
	v_rcp_f32_e32 v25, v9
	v_pk_fma_f32 v[8:9], v[10:11], v[44:45], v[22:23]
	v_lshlrev_b32_e32 v22, 16, v7
	v_and_b32_e32 v23, 0xffff0000, v7
	v_pk_fma_f32 v[4:5], v[4:5], v[22:23], v[16:17]
	v_lshlrev_b32_e32 v22, 16, v6
	v_mul_f32_e32 v7, 0xbfb8aa3b, v4
	v_exp_f32_e32 v7, v7
	v_and_b32_e32 v23, 0xffff0000, v6
	v_pk_fma_f32 v[2:3], v[2:3], v[22:23], v[14:15]
	v_mul_f32_e32 v10, 0xbfb8aa3b, v8
	v_add_f32_e32 v7, 1.0, v7
	v_rcp_f32_e32 v16, v7
	v_mul_f32_e32 v7, 0xbfb8aa3b, v5
	v_exp_f32_e32 v7, v7
	v_mul_f32_e32 v6, 0xbfb8aa3b, v2
	v_exp_f32_e32 v6, v6
	v_mul_f32_e32 v11, 0xbfb8aa3b, v9
	v_add_f32_e32 v7, 1.0, v7
	v_rcp_f32_e32 v17, v7
	v_mul_f32_e32 v7, 0xbfb8aa3b, v3
	v_exp_f32_e32 v7, v7
	v_exp_f32_e32 v10, v10
	v_exp_f32_e32 v11, v11
	v_add_f32_e32 v6, 1.0, v6
	v_add_f32_e32 v7, 1.0, v7
	v_rcp_f32_e32 v6, v6
	v_rcp_f32_e32 v7, v7
	v_and_b32_e32 v39, 0xffff0000, v49
	v_mul_f32_e32 v40, 0xbfb8aa3b, v28
	v_mul_f32_e32 v41, 0xbfb8aa3b, v29
	v_pk_fma_f32 v[34:35], v[46:47], v[38:39], v[34:35]
	v_exp_f32_e32 v40, v40
	v_exp_f32_e32 v41, v41
	v_add_f32_e32 v10, 1.0, v10
	v_add_f32_e32 v11, 1.0, v11
	v_mul_f32_e32 v38, 0xbfb8aa3b, v34
	v_mul_f32_e32 v39, 0xbfb8aa3b, v35
	v_rcp_f32_e32 v10, v10
	v_rcp_f32_e32 v11, v11
	v_exp_f32_e32 v38, v38
	v_exp_f32_e32 v39, v39
	v_pk_mul_f32 v[6:7], v[2:3], v[6:7]
	v_mul_f32_e32 v36, 0xbfb8aa3b, v30
	v_mul_f32_e32 v37, 0xbfb8aa3b, v31
	v_pk_mul_f32 v[4:5], v[4:5], v[16:17]
	v_pk_mul_f32 v[2:3], v[6:7], v[6:7]
	v_exp_f32_e32 v36, v36
	v_exp_f32_e32 v37, v37
	v_add_f32_e32 v40, 1.0, v40
	v_add_f32_e32 v41, 1.0, v41
	v_pk_mul_f32 v[16:17], v[4:5], v[4:5]
	v_add_f32_e32 v2, v2, v3
	v_mul_f32_e32 v32, 0xbfb8aa3b, v26
	v_mul_f32_e32 v33, 0xbfb8aa3b, v27
	v_rcp_f32_e32 v40, v40
	v_rcp_f32_e32 v41, v41
	v_pk_mul_f32 v[8:9], v[8:9], v[10:11]
	v_add_f32_e32 v2, v16, v2
	v_exp_f32_e32 v32, v32
	v_exp_f32_e32 v33, v33
	v_add_f32_e32 v38, 1.0, v38
	v_add_f32_e32 v39, 1.0, v39
	v_pk_mul_f32 v[10:11], v[8:9], v[8:9]
	v_add_f32_e32 v2, v17, v2
	v_rcp_f32_e32 v38, v38
	v_rcp_f32_e32 v39, v39
	v_pk_mul_f32 v[12:13], v[12:13], v[24:25]
	v_add_f32_e32 v2, v10, v2
	v_add_f32_e32 v36, 1.0, v36
	v_add_f32_e32 v37, 1.0, v37
	v_pk_mul_f32 v[24:25], v[12:13], v[12:13]
	v_add_f32_e32 v2, v11, v2
	v_rcp_f32_e32 v36, v36
	v_rcp_f32_e32 v37, v37
	v_pk_mul_f32 v[28:29], v[28:29], v[40:41]
	v_add_f32_e32 v2, v24, v2
	v_add_f32_e32 v32, 1.0, v32
	v_add_f32_e32 v33, 1.0, v33
	v_pk_mul_f32 v[40:41], v[28:29], v[28:29]
	v_add_f32_e32 v2, v25, v2
	v_rcp_f32_e32 v32, v32
	v_rcp_f32_e32 v33, v33
	v_pk_mul_f32 v[34:35], v[34:35], v[38:39]
	v_add_f32_e32 v2, v40, v2
	v_pk_mul_f32 v[38:39], v[34:35], v[34:35]
	v_add_f32_e32 v2, v41, v2
	v_pk_mul_f32 v[30:31], v[30:31], v[36:37]
	v_add_f32_e32 v2, v38, v2
	v_pk_mul_f32 v[36:37], v[30:31], v[30:31]
	v_add_f32_e32 v2, v39, v2
	v_pk_mul_f32 v[26:27], v[26:27], v[32:33]
	v_add_f32_e32 v2, v36, v2
	v_pk_mul_f32 v[32:33], v[26:27], v[26:27]
	v_add_f32_e32 v2, v37, v2
	v_add_f32_e32 v2, v32, v2
	v_add_f32_e32 v2, v33, v2
	s_nop 1
	v_add_f32_dpp v2, v2, v2 quad_perm:[1,0,3,2] row_mask:0xf bank_mask:0xf bound_ctrl:1
	s_nop 1
	v_add_f32_dpp v2, v2, v2 quad_perm:[2,3,0,1] row_mask:0xf bank_mask:0xf bound_ctrl:1
	s_nop 1
	v_add_f32_dpp v2, v2, v2 row_half_mirror row_mask:0xf bank_mask:0xf bound_ctrl:1
	v_add_f32_e32 v2, 0x358637bd, v2
	v_rsq_f32_e32 v10, v2
	v_mov_b32_e32 v2, 0
	v_mov_b32_e32 v32, v2
	v_mov_b32_e32 v33, v2
; #define LAS __attribute__((address_space(3)))
; __device__ __forceinline__ unsigned f2bf(float f) { return pk2(f, f) & 0xffffu; }
; __device__ __forceinline__ void gdn_prep_wg(const bf16* P, const float* SMALL, const float* conv_w, const float* a_log, const float* dt_bias,
;                                             unsigned char* REC, bf16* UF, float* EG, LAS unsigned char* lds, int bh, int n0, int nch) {
;     ...
;                 if (ten < 2) { ss = sum8(ss); const float s_ = (1.0f / sqrtf(ss + EPS)) * (ten == 0 ? 0.08838834764831845f : 1.0f);
; #pragma unroll
;                     for (int j = 0; j < 16; ++j) acc[j] *= s_; }
;                 if (ten == 0) {
;                     v4u o0, o1; o0.x = pk2(acc[0], acc[1]); o0.y = pk2(acc[2], acc[3]); o0.z = pk2(acc[4], acc[5]); o0.w = pk2(acc[6], acc[7]);
;                     o1.x = pk2(acc[8], acc[9]); o1.y = pk2(acc[10], acc[11]); o1.z = pk2(acc[12], acc[13]); o1.w = pk2(acc[14], acc[15]);
;                     *(LAS v4u*)(qb + row * 272 + c0 * 2) = o0; *(LAS v4u*)(qb + row * 272 + c0 * 2 + 16) = o1;
;                     unsigned char* dst = rec + GR_Q + ((row >> 4) * 4 + (c0 >> 5)) * 1024 + ((c0 >> 4) & 1) * 8;
; #pragma unroll
;                     for (int i = 0; i < 4; ++i) { v2u w; w.x = pk2(acc[4 * i] * egc, acc[4 * i + 1] * egc); w.y = pk2(acc[4 * i + 2] * egc, acc[4 * i + 3] * egc);
;                         *(v2u*)(dst + ((row & 15) + 16 * i) * 16) = w; }
;                 } else if (ten == 1) {
;                     v4u o0, o1; o0.x = pk2(acc[0], acc[1]); o0.y = pk2(acc[2], acc[3]); o0.z = pk2(acc[4], acc[5]); o0.w = pk2(acc[6], acc[7]);
;                     o1.x = pk2(acc[8], acc[9]); o1.y = pk2(acc[10], acc[11]); o1.z = pk2(acc[12], acc[13]); o1.w = pk2(acc[14], acc[15]);
;                     *(LAS v4u*)(kb + row * 272 + c0 * 2) = o0; *(LAS v4u*)(kb + row * 272 + c0 * 2 + 16) = o1;
;                     const float bg = be * egc; const int off = row & 31, kq = (off & 15) >> 2, kj = (off & 3) + 4 * (off >> 4);
;                     unsigned char* dst = rec + GR_K + ((c0 >> 4) * 2 + (row >> 5)) * 1024 + (16 * kq) * 16 + kj * 2;
; #pragma unroll
;                     for (int e = 0; e < 16; ++e) { *(LAS bf16*)(RT + (128 + c0 + e) * 144 + row * 2) = (bf16)f2bf(acc[e] * bg);
;                         *(bf16*)(dst + e * 16) = (bf16)f2bf(acc[e] * egl); }
	v_pk_mul_f32 v[14:15], v[6:7], v[10:11] op_sel_hi:[1,0]
	v_pk_mul_f32 v[16:17], v[4:5], v[10:11] op_sel_hi:[1,0]
	v_pk_mul_f32 v[22:23], v[8:9], v[10:11] op_sel_hi:[1,0]
	v_pk_mul_f32 v[12:13], v[12:13], v[10:11] op_sel_hi:[1,0]
	v_mul_f32_e32 v3, v19, v14
	v_pk_mul_f32 v[24:25], v[28:29], v[10:11] op_sel_hi:[1,0]
	v_pk_mul_f32 v[28:29], v[34:35], v[10:11] op_sel_hi:[1,0]
	v_pk_mul_f32 v[30:31], v[30:31], v[10:11] op_sel_hi:[1,0]
	v_pk_mul_f32 v[26:27], v[26:27], v[10:11] op_sel_hi:[1,0]
	v_cvt_pk_bf16_f32 v4, v14, v15
	v_cvt_pk_bf16_f32 v5, v16, v17
	v_cvt_pk_bf16_f32 v6, v22, v23
	v_cvt_pk_bf16_f32 v7, v12, v13
	v_cvt_pk_bf16_f32 v3, v3, s0
	v_cvt_pk_bf16_f32 v8, v24, v25
	v_cvt_pk_bf16_f32 v9, v28, v29
	v_cvt_pk_bf16_f32 v10, v30, v31
	v_cvt_pk_bf16_f32 v11, v26, v27
	ds_write_b128 v43, v[4:7]
	ds_write_b128 v43, v[8:11] offset:16
	ds_write_b16 v192, v3 offset:53248
	v_and_b32_e32 v236, 7, v0
	v_lshrrev_b32_e32 v237, 3, v0
	v_lshrrev_b32_e32 v238, 5, v237
	v_lshl_add_u32 v238, v236, 1, v238
	v_lshlrev_b32_e32 v235, 4, v238
	v_lshl_add_u32 v239, v238, 10, v235
	v_bfe_u32 v238, v237, 2, 2
	v_lshl_add_u32 v239, v238, 8, v239
	v_and_b32_e32 v238, 3, v237
	v_lshl_add_u32 v239, v238, 1, v239
	v_bfe_u32 v238, v237, 4, 1
	v_lshl_add_u32 v239, v238, 3, v239
	v_add_u32_e32 v239, 0x11800, v239
	v_mul_f32_e32 v3, v42, v14
	v_cvt_pk_bf16_f32 v3, v3, s0
	ds_write_b16 v239, v3
	v_mul_f32_e32 v3, v19, v15
	v_cvt_pk_bf16_f32 v3, v3, s0
	ds_write_b16 v192, v3 offset:53392
	v_mul_f32_e32 v3, v42, v15
	v_cvt_pk_bf16_f32 v3, v3, s0
	ds_write_b16 v239, v3 offset:16
	v_mul_f32_e32 v3, v19, v16
	v_cvt_pk_bf16_f32 v3, v3, s0
	ds_write_b16 v192, v3 offset:53536
	v_mul_f32_e32 v3, v42, v16
	v_cvt_pk_bf16_f32 v3, v3, s0
	ds_write_b16 v239, v3 offset:32
	v_mul_f32_e32 v3, v19, v17
	v_cvt_pk_bf16_f32 v3, v3, s0
	ds_write_b16 v192, v3 offset:53680
	v_mul_f32_e32 v3, v42, v17
	v_cvt_pk_bf16_f32 v3, v3, s0
	ds_write_b16 v239, v3 offset:48
	v_mul_f32_e32 v3, v19, v22
	v_cvt_pk_bf16_f32 v3, v3, s0
	ds_write_b16 v192, v3 offset:53824
	v_mul_f32_e32 v3, v42, v22
	v_cvt_pk_bf16_f32 v3, v3, s0
	ds_write_b16 v239, v3 offset:64
	v_mul_f32_e32 v3, v19, v23
	v_cvt_pk_bf16_f32 v3, v3, s0
	ds_write_b16 v192, v3 offset:53968
	v_mul_f32_e32 v3, v42, v23
	v_cvt_pk_bf16_f32 v3, v3, s0
	ds_write_b16 v239, v3 offset:80
	v_mul_f32_e32 v3, v19, v12
	v_cvt_pk_bf16_f32 v3, v3, s0
	ds_write_b16 v192, v3 offset:54112
	v_mul_f32_e32 v3, v42, v12
	v_cvt_pk_bf16_f32 v3, v3, s0
	ds_write_b16 v239, v3 offset:96
	v_mul_f32_e32 v3, v19, v13
	v_cvt_pk_bf16_f32 v3, v3, s0
	ds_write_b16 v192, v3 offset:54256
	v_mul_f32_e32 v3, v42, v13
	v_cvt_pk_bf16_f32 v3, v3, s0
	ds_write_b16 v239, v3 offset:112
	v_mul_f32_e32 v3, v19, v24
	v_cvt_pk_bf16_f32 v3, v3, s0
	ds_write_b16 v192, v3 offset:54400
	v_mul_f32_e32 v3, v42, v24
	v_cvt_pk_bf16_f32 v3, v3, s0
	ds_write_b16 v239, v3 offset:128
	v_mul_f32_e32 v3, v19, v25
	v_cvt_pk_bf16_f32 v3, v3, s0
	ds_write_b16 v192, v3 offset:54544
	v_mul_f32_e32 v3, v42, v25
	v_cvt_pk_bf16_f32 v3, v3, s0
	ds_write_b16 v239, v3 offset:144
	v_mul_f32_e32 v3, v19, v28
	v_cvt_pk_bf16_f32 v3, v3, s0
	ds_write_b16 v192, v3 offset:54688
	v_mul_f32_e32 v3, v42, v28
	v_cvt_pk_bf16_f32 v3, v3, s0
	ds_write_b16 v239, v3 offset:160
	v_mul_f32_e32 v3, v19, v29
	v_cvt_pk_bf16_f32 v3, v3, s0
	ds_write_b16 v192, v3 offset:54832
	v_mul_f32_e32 v3, v42, v29
	v_cvt_pk_bf16_f32 v3, v3, s0
	ds_write_b16 v239, v3 offset:176
	v_mul_f32_e32 v3, v19, v30
	v_cvt_pk_bf16_f32 v3, v3, s0
	ds_write_b16 v192, v3 offset:54976
	v_mul_f32_e32 v3, v42, v30
	v_cvt_pk_bf16_f32 v3, v3, s0
	ds_write_b16 v239, v3 offset:192
	v_mul_f32_e32 v3, v19, v31
	v_cvt_pk_bf16_f32 v3, v3, s0
	ds_write_b16 v192, v3 offset:55120
	v_mul_f32_e32 v3, v42, v31
	v_cvt_pk_bf16_f32 v3, v3, s0
	ds_write_b16 v239, v3 offset:208
	v_mul_f32_e32 v3, v19, v26
	v_cvt_pk_bf16_f32 v3, v3, s0
	ds_write_b16 v192, v3 offset:55264
	v_mul_f32_e32 v3, v42, v26
	v_cvt_pk_bf16_f32 v3, v3, s0
	ds_write_b16 v239, v3 offset:224
	v_mul_f32_e32 v3, v19, v27
	v_cvt_pk_bf16_f32 v3, v3, s0
	ds_write_b16 v192, v3 offset:55408
	v_mul_f32_e32 v3, v42, v27
	v_cvt_pk_bf16_f32 v3, v3, s0
	ds_write_b16 v239, v3 offset:240
	v_mov_b32_e32 v3, 0
	v_mov_b32_e32 v20, 0
	v_mov_b32_e32 v21, 0
	v_mov_b32_e32 v22, 0
	v_mov_b32_e32 v23, v2
	v_mov_b32_e32 v24, v2
	v_mov_b32_e32 v25, v2
	v_mov_b32_e32 v26, v2
	v_mov_b32_e32 v27, v2
	v_mov_b32_e32 v28, v2
	v_mov_b32_e32 v29, v2
	v_mov_b32_e32 v30, v2
	v_mov_b32_e32 v31, v2
	v_mov_b32_e32 v34, 0
	v_mov_b32_e32 v35, 0
	s_and_saveexec_b64 s[90:91], s[86:87]
	s_cbranch_execnz .LBB0_381
	s_or_b64 exec, exec, s[90:91]
	s_and_saveexec_b64 s[86:87], s[88:89]
	s_cbranch_execnz .LBB0_382
